# v19 plus retention scores-section de-serialisation and norm-phase (sub 0) invariant weight loads hoisted out of the row loop
# baseline (speedup 1.0000x reference)
.LBB0_140:
	s_andn2_b64 vcc, exec, s[14:15]
	s_cbranch_vccnz .LBB0_145
	v_readlane_b32 s14, v255, 4
	v_readlane_b32 s15, v255, 5
	s_lshl_b64 s[14:15], s[14:15], 3
	v_readlane_b32 s18, v253, 9
	s_or_b32 s14, s14, s18
	s_mul_i32 s15, s15, 0x9000
	s_mul_hi_u32 s18, s14, 0x9000
	s_add_i32 s18, s18, s15
	s_mul_i32 s14, s14, 0x9000
	s_add_u32 s14, s38, s14
	v_ashrrev_i32_e32 v75, 31, v74
	s_addc_u32 s15, s39, s18
	v_lshlrev_b64 v[2:3], 4, v[74:75]
	v_lshl_add_u64 v[68:69], v[74:75], 3, s[0:1]
	v_lshl_add_u64 v[72:73], s[14:15], 0, v[2:3]
	s_mov_b64 s[0:1], 0x1000
	v_lshlrev_b32_e32 v4, 2, v74
	v_lshl_add_u64 v[74:75], v[72:73], 0, s[0:1]
	s_mov_b64 s[0:1], 0x1400
	v_lshl_add_u64 v[76:77], v[72:73], 0, s[0:1]
	s_mov_b64 s[0:1], 0x1800
	v_lshl_add_u64 v[78:79], v[72:73], 0, s[0:1]
	s_mov_b64 s[0:1], 0x1c00
	v_lshl_add_u64 v[66:67], s[44:45], 0, v[2:3]
	v_xor_b32_e32 v0, 4, v4
	v_xor_b32_e32 v82, 8, v4
	v_xor_b32_e32 v83, 16, v4
	v_xor_b32_e32 v84, 32, v4
	v_xor_b32_e32 v85, 64, v4
	v_xor_b32_e32 v86, 0x80, v4
	v_lshl_add_u64 v[70:71], s[10:11], 0, v[2:3]
	v_lshl_add_u64 v[80:81], v[72:73], 0, s[0:1]
	s_mov_b32 s20, 0
	v_readlane_b32 s21, v253, 8
	v_readlane_b32 s34, v254, 52
	global_load_dwordx4 v[108:111], v[74:75], off
	global_load_dwordx4 v[112:115], v[70:71], off
	global_load_dwordx4 v[116:119], v[72:73], off
	global_load_dwordx4 v[120:123], v[70:71], off offset:1024
	global_load_dwordx4 v[124:127], v[76:77], off
	global_load_dwordx4 v[128:131], v[72:73], off offset:1024
	global_load_dwordx4 v[132:135], v[70:71], off offset:2048
	global_load_dwordx4 v[136:139], v[78:79], off
	global_load_dwordx4 v[140:143], v[72:73], off offset:2048
	global_load_dwordx4 v[144:147], v[70:71], off offset:3072
	global_load_dwordx4 v[148:151], v[80:81], off
	global_load_dwordx4 v[152:155], v[72:73], off offset:3072
	s_waitcnt vmcnt(0)
	s_branch .LBB0_143

.LBB0_143:
	s_cmpk_gt_i32 s21, 0x1fff
	s_cbranch_scc1 .LBB0_142
	s_add_i32 s18, s27, s21
	s_add_i32 s0, s54, s21
	s_cmpk_lt_i32 s0, 0x2000
	s_cselect_b32 s0, s0, s21
	s_add_i32 s14, s0, s27
	s_add_i32 s0, s34, s21
	s_cmpk_lt_i32 s0, 0x2000
	s_cselect_b32 s0, s0, s21
	s_mul_i32 s1, s54, 3
	s_add_i32 s0, s0, s27
	s_add_i32 s1, s1, s21
	s_cmpk_lt_i32 s1, 0x2000
	s_cselect_b32 s10, s1, s21
	s_ashr_i32 s19, s18, 31
	s_lshl_b64 s[22:23], s[18:19], 12
	v_lshl_add_u64 v[2:3], v[66:67], 0, s[22:23]
	global_load_dwordx4 v[46:49], v[2:3], off nt
	global_load_dwordx4 v[42:45], v[2:3], off offset:1024 nt
	global_load_dwordx4 v[34:37], v[2:3], off offset:3072 nt
	global_load_dwordx4 v[38:41], v[2:3], off offset:2048 nt
	s_ashr_i32 s15, s14, 31
	s_lshl_b64 s[22:23], s[14:15], 12
	s_ashr_i32 s1, s0, 31
	s_lshl_b64 s[24:25], s[0:1], 12
	s_add_i32 s10, s10, s27
	s_lshl_b64 s[18:19], s[18:19], 11
	s_ashr_i32 s11, s10, 31
	v_lshl_add_u64 v[100:101], v[68:69], 0, s[18:19]
	s_lshl_b64 s[18:19], s[10:11], 12
	s_lshl_b64 s[14:15], s[14:15], 11
	s_lshl_b64 s[0:1], s[0:1], 11
	s_waitcnt vmcnt(3)
	v_pk_mul_f32 v[2:3], v[48:49], v[48:49]
	v_pk_mul_f32 v[4:5], v[46:47], v[46:47]
	s_waitcnt vmcnt(2)
	v_pk_mul_f32 v[6:7], v[44:45], v[44:45]
	v_pk_mul_f32 v[8:9], v[42:43], v[42:43]
	v_pk_mov_b32 v[14:15], v[4:5], v[2:3] op_sel:[1, 0]
	v_mov_b32_e32 v5, v3
	v_pk_mov_b32 v[2:3], v[8:9], v[6:7] op_sel:[1, 0]
	v_mov_b32_e32 v9, v7
	s_waitcnt vmcnt(1)
	v_mul_f32_e32 v13, v34, v34
	s_waitcnt vmcnt(0)
	v_mul_f32_e32 v10, v39, v39
	v_mul_f32_e32 v12, v41, v41
	v_pk_add_f32 v[4:5], v[14:15], v[4:5]
	v_pk_add_f32 v[2:3], v[2:3], v[8:9]
	v_mul_f32_e32 v16, v35, v35
	v_mul_f32_e32 v17, v36, v36
	v_mul_f32_e32 v18, v37, v37
	v_pk_fma_f32 v[6:7], v[38:39], v[38:39], v[10:11] op_sel_hi:[1, 1, 0]
	v_pk_fma_f32 v[10:11], v[40:41], v[40:41], v[12:13] op_sel_hi:[1, 1, 0]
	v_pk_add_f32 v[4:5], v[4:5], v[4:5] op_sel:[0, 1] op_sel_hi:[1, 0]
	v_pk_add_f32 v[2:3], v[2:3], v[2:3] op_sel:[0, 1] op_sel_hi:[1, 0]
	v_mov_b32_e32 v7, v17
	v_mov_b32_e32 v11, v18
	v_mov_b32_e32 v5, v13
	v_mov_b32_e32 v3, v16
	v_pk_add_f32 v[6:7], v[6:7], v[10:11]
	v_pk_add_f32 v[2:3], v[4:5], v[2:3]
	v_lshl_add_u64 v[4:5], v[66:67], 0, s[24:25]
	v_pk_add_f32 v[2:3], v[2:3], v[6:7]
	v_pk_add_f32 v[88:89], v[108:109], 1.0 op_sel_hi:[1, 0]
	v_add_f32_e32 v2, v2, v3
	ds_bpermute_b32 v3, v0, v2
	v_pk_add_f32 v[90:91], v[110:111], 1.0 op_sel_hi:[1, 0]
	s_waitcnt lgkmcnt(0)
	v_add_f32_e32 v2, v2, v3
	ds_bpermute_b32 v3, v82, v2
	s_waitcnt lgkmcnt(0)
	v_add_f32_e32 v6, v2, v3
	ds_bpermute_b32 v7, v83, v6
	v_lshl_add_u64 v[2:3], v[66:67], 0, s[22:23]
	global_load_dwordx4 v[62:65], v[2:3], off nt
	global_load_dwordx4 v[58:61], v[2:3], off offset:1024 nt
	global_load_dwordx4 v[54:57], v[2:3], off offset:2048 nt
	global_load_dwordx4 v[50:53], v[2:3], off offset:3072 nt
	global_load_dwordx4 v[30:33], v[4:5], off nt
	global_load_dwordx4 v[26:29], v[4:5], off offset:1024 nt
	global_load_dwordx4 v[22:25], v[4:5], off offset:2048 nt
	global_load_dwordx4 v[18:21], v[4:5], off offset:3072 nt
	s_waitcnt lgkmcnt(0)
	v_add_f32_e32 v6, v6, v7
	ds_bpermute_b32 v7, v84, v6
	s_waitcnt lgkmcnt(0)
	v_add_f32_e32 v2, v6, v7
	ds_bpermute_b32 v3, v85, v2
	s_waitcnt lgkmcnt(0)
	v_add_f32_e32 v4, v2, v3
	ds_bpermute_b32 v5, v86, v4
	v_lshl_add_u64 v[2:3], v[66:67], 0, s[18:19]
	global_load_dwordx4 v[14:17], v[2:3], off nt
	global_load_dwordx4 v[10:13], v[2:3], off offset:1024 nt
	s_waitcnt lgkmcnt(0)
	v_add_f32_e32 v4, v4, v5
	v_fmamk_f32 v4, v4, 0x3a800000, v207
	v_mul_f32_e32 v5, 0x4f800000, v4
	v_cmp_gt_f32_e32 vcc, s82, v4
	s_nop 1
	v_cndmask_b32_e32 v87, v4, v5, vcc
	v_sqrt_f32_e32 v102, v87
	global_load_dwordx4 v[6:9], v[2:3], off offset:2048 nt
	s_nop 0
	global_load_dwordx4 v[2:5], v[2:3], off offset:3072 nt
	v_add_u32_e32 v103, -1, v102
	v_add_u32_e32 v104, 1, v102
	v_fma_f32 v105, -v103, v102, v87
	v_fma_f32 v106, -v104, v102, v87
	v_cmp_ge_f32_e64 s[36:37], 0, v105
	s_nop 1
	v_cndmask_b32_e64 v102, v102, v103, s[36:37]
	v_cmp_lt_f32_e64 s[36:37], 0, v106
	s_nop 1
	v_cndmask_b32_e64 v102, v102, v104, s[36:37]
	v_mul_f32_e32 v103, 0x37800000, v102
	v_cndmask_b32_e32 v102, v102, v103, vcc
	v_cmp_class_f32_e32 vcc, v87, v227
	s_nop 1
	v_cndmask_b32_e32 v87, v102, v87, vcc
	v_div_scale_f32 v102, s[18:19], v87, v87, 1.0
	v_rcp_f32_e32 v103, v102
	v_div_scale_f32 v104, vcc, 1.0, v87, 1.0
	v_fma_f32 v105, -v102, v103, 1.0
	v_fmac_f32_e32 v103, v105, v103
	v_mul_f32_e32 v105, v104, v103
	v_fma_f32 v106, -v102, v105, v104
	v_fmac_f32_e32 v105, v106, v103
	v_fma_f32 v102, -v102, v105, v104
	v_div_fmas_f32 v102, v102, v103, v105
	v_div_fixup_f32 v102, v102, v87, 1.0
	v_pk_mul_f32 v[46:47], v[46:47], v[102:103] op_sel_hi:[1, 0]
	v_pk_mul_f32 v[48:49], v[48:49], v[102:103] op_sel_hi:[1, 0]
	v_pk_mul_f32 v[46:47], v[112:113], v[46:47]
	v_pk_mul_f32 v[48:49], v[114:115], v[48:49]
	v_pk_fma_f32 v[46:47], v[88:89], v[46:47], v[116:117]
	v_pk_fma_f32 v[48:49], v[90:91], v[48:49], v[118:119]
	v_cvt_pk_bf16_f32 v46, v46, v47
	v_pk_mul_f32 v[44:45], v[44:45], v[102:103] op_sel_hi:[1, 0]
	v_cvt_pk_bf16_f32 v47, v48, v49
	global_store_dwordx2 v[100:101], v[46:47], off
	s_nop 0
	v_pk_mul_f32 v[42:43], v[42:43], v[102:103] op_sel_hi:[1, 0]
	v_pk_mul_f32 v[40:41], v[40:41], v[102:103] op_sel_hi:[1, 0]
	v_pk_mul_f32 v[38:39], v[38:39], v[102:103] op_sel_hi:[1, 0]
	s_waitcnt vmcnt(10)
	v_mul_f32_e32 v96, v55, v55
	s_waitcnt vmcnt(9)
	v_mul_f32_e32 v103, v52, v52
	v_pk_mul_f32 v[36:37], v[36:37], v[102:103] op_sel_hi:[1, 0]
	v_pk_mul_f32 v[34:35], v[34:35], v[102:103] op_sel_hi:[1, 0]
	v_mul_f32_e32 v99, v51, v51
	v_mul_f32_e32 v98, v57, v57
	v_mul_f32_e32 v87, v50, v50
	v_mul_f32_e32 v106, v53, v53
	s_waitcnt vmcnt(1)
	v_pk_mul_f32 v[42:43], v[42:43], v[120:121]
	v_pk_mul_f32 v[44:45], v[44:45], v[122:123]
	v_pk_add_f32 v[48:49], v[124:125], 1.0 op_sel_hi:[1, 0]
	v_pk_add_f32 v[46:47], v[126:127], 1.0 op_sel_hi:[1, 0]
	v_pk_fma_f32 v[42:43], v[42:43], v[48:49], v[128:129]
	v_pk_fma_f32 v[44:45], v[44:45], v[46:47], v[130:131]
	v_cvt_pk_bf16_f32 v42, v42, v43
	v_pk_mul_f32 v[92:93], v[60:61], v[60:61]
	v_cvt_pk_bf16_f32 v43, v44, v45
	global_store_dwordx2 v[100:101], v[42:43], off offset:512
	s_nop 0
	v_pk_mul_f32 v[94:95], v[58:59], v[58:59]
	v_pk_mul_f32 v[38:39], v[38:39], v[132:133]
	v_pk_mul_f32 v[40:41], v[40:41], v[134:135]
	v_pk_add_f32 v[44:45], v[136:137], 1.0 op_sel_hi:[1, 0]
	v_pk_add_f32 v[42:43], v[138:139], 1.0 op_sel_hi:[1, 0]
	v_pk_fma_f32 v[38:39], v[38:39], v[44:45], v[140:141]
	v_pk_fma_f32 v[40:41], v[40:41], v[42:43], v[142:143]
	v_cvt_pk_bf16_f32 v38, v38, v39
	v_pk_mul_f32 v[88:89], v[64:65], v[64:65]
	v_cvt_pk_bf16_f32 v39, v40, v41
	global_store_dwordx2 v[100:101], v[38:39], off offset:1024
	s_nop 0
	v_pk_mul_f32 v[90:91], v[62:63], v[62:63]
	v_pk_mul_f32 v[34:35], v[34:35], v[144:145]
	v_pk_mul_f32 v[36:37], v[36:37], v[146:147]
	v_pk_add_f32 v[40:41], v[148:149], 1.0 op_sel_hi:[1, 0]
	v_pk_add_f32 v[38:39], v[150:151], 1.0 op_sel_hi:[1, 0]
	v_pk_fma_f32 v[34:35], v[34:35], v[40:41], v[152:153]
	v_pk_fma_f32 v[36:37], v[36:37], v[38:39], v[154:155]
	v_cvt_pk_bf16_f32 v34, v34, v35
	v_pk_mov_b32 v[104:105], v[90:91], v[88:89] op_sel:[1, 0]
	v_cvt_pk_bf16_f32 v35, v36, v37
	global_store_dwordx2 v[100:101], v[34:35], off offset:1536
	v_mov_b32_e32 v91, v89
	v_pk_mov_b32 v[88:89], v[94:95], v[92:93] op_sel:[1, 0]
	v_mov_b32_e32 v95, v93
	v_pk_add_f32 v[90:91], v[104:105], v[90:91]
	v_pk_add_f32 v[88:89], v[88:89], v[94:95]
	v_mov_b32_e32 v97, v117
	v_pk_fma_f32 v[92:93], v[54:55], v[54:55], v[96:97] op_sel_hi:[1, 1, 0]
	v_pk_fma_f32 v[96:97], v[56:57], v[56:57], v[98:99] op_sel_hi:[1, 1, 0]
	v_pk_add_f32 v[90:91], v[90:91], v[90:91] op_sel:[0, 1] op_sel_hi:[1, 0]
	v_pk_add_f32 v[88:89], v[88:89], v[88:89] op_sel:[0, 1] op_sel_hi:[1, 0]
	v_mov_b32_e32 v93, v103
	v_mov_b32_e32 v97, v106
	v_mov_b32_e32 v91, v87
	v_mov_b32_e32 v89, v99
	v_pk_add_f32 v[92:93], v[92:93], v[96:97]
	v_pk_add_f32 v[46:47], v[90:91], v[88:89]
	v_pk_add_f32 v[38:39], v[108:109], 1.0 op_sel_hi:[1, 0]
	v_pk_add_f32 v[46:47], v[46:47], v[92:93]
	v_pk_add_f32 v[40:41], v[110:111], 1.0 op_sel_hi:[1, 0]
	v_add_f32_e32 v46, v46, v47
	ds_bpermute_b32 v47, v0, v46
	s_waitcnt lgkmcnt(0)
	v_add_f32_e32 v46, v46, v47
	ds_bpermute_b32 v47, v82, v46
	s_waitcnt lgkmcnt(0)
	v_add_f32_e32 v46, v46, v47
	ds_bpermute_b32 v47, v83, v46
	s_waitcnt lgkmcnt(0)
	v_add_f32_e32 v46, v46, v47
	ds_bpermute_b32 v47, v84, v46
	s_waitcnt lgkmcnt(0)
	v_add_f32_e32 v46, v46, v47
	ds_bpermute_b32 v47, v85, v46
	s_waitcnt lgkmcnt(0)
	v_add_f32_e32 v46, v46, v47
	ds_bpermute_b32 v47, v86, v46
	s_waitcnt lgkmcnt(0)
	v_add_f32_e32 v46, v46, v47
	v_fmamk_f32 v46, v46, 0x3a800000, v207
	v_mul_f32_e32 v47, 0x4f800000, v46
	v_cmp_gt_f32_e32 vcc, s82, v46
	s_nop 1
	v_cndmask_b32_e32 v46, v46, v47, vcc
	v_sqrt_f32_e32 v47, v46
	s_nop 0
	v_add_u32_e32 v48, -1, v47
	v_add_u32_e32 v49, 1, v47
	v_fma_f32 v87, -v48, v47, v46
	v_fma_f32 v88, -v49, v47, v46
	v_cmp_ge_f32_e64 s[36:37], 0, v87
	s_nop 1
	v_cndmask_b32_e64 v47, v47, v48, s[36:37]
	v_cmp_lt_f32_e64 s[36:37], 0, v88
	s_nop 1
	v_cndmask_b32_e64 v47, v47, v49, s[36:37]
	v_mul_f32_e32 v48, 0x37800000, v47
	v_cndmask_b32_e32 v47, v47, v48, vcc
	v_cmp_class_f32_e32 vcc, v46, v227
	s_nop 1
	v_cndmask_b32_e32 v48, v47, v46, vcc
	v_div_scale_f32 v49, s[18:19], v48, v48, 1.0
	v_rcp_f32_e32 v87, v49
	v_div_scale_f32 v88, vcc, 1.0, v48, 1.0
	v_lshl_add_u64 v[46:47], v[68:69], 0, s[14:15]
	v_fma_f32 v89, -v49, v87, 1.0
	v_fmac_f32_e32 v87, v89, v87
	v_mul_f32_e32 v89, v88, v87
	v_fma_f32 v90, -v49, v89, v88
	v_fmac_f32_e32 v89, v90, v87
	v_fma_f32 v49, -v49, v89, v88
	v_div_fmas_f32 v49, v49, v87, v89
	v_div_fixup_f32 v48, v49, v48, 1.0
	v_pk_mul_f32 v[62:63], v[62:63], v[48:49] op_sel_hi:[1, 0]
	v_pk_mul_f32 v[64:65], v[64:65], v[48:49] op_sel_hi:[1, 0]
	v_pk_mul_f32 v[34:35], v[62:63], v[112:113]
	v_pk_mul_f32 v[36:37], v[64:65], v[114:115]
	v_pk_fma_f32 v[34:35], v[34:35], v[38:39], v[116:117]
	v_pk_fma_f32 v[36:37], v[36:37], v[40:41], v[118:119]
	v_cvt_pk_bf16_f32 v34, v34, v35
	v_pk_mul_f32 v[58:59], v[58:59], v[48:49] op_sel_hi:[1, 0]
	v_cvt_pk_bf16_f32 v35, v36, v37
	global_store_dwordx2 v[46:47], v[34:35], off
	s_nop 0
	v_pk_mul_f32 v[60:61], v[60:61], v[48:49] op_sel_hi:[1, 0]
	v_pk_mul_f32 v[54:55], v[54:55], v[48:49] op_sel_hi:[1, 0]
	v_pk_mul_f32 v[56:57], v[56:57], v[48:49] op_sel_hi:[1, 0]
	v_mul_f32_e32 v49, v18, v18
	v_pk_mul_f32 v[52:53], v[52:53], v[48:49] op_sel_hi:[1, 0]
	v_mul_f32_e32 v65, v19, v19
	v_mul_f32_e32 v62, v23, v23
	v_mul_f32_e32 v64, v25, v25
	v_mul_f32_e32 v87, v20, v20
	v_mul_f32_e32 v90, v21, v21
	v_pk_mul_f32 v[34:35], v[58:59], v[120:121]
	v_pk_add_f32 v[38:39], v[124:125], 1.0 op_sel_hi:[1, 0]
	v_pk_mul_f32 v[36:37], v[60:61], v[122:123]
	v_pk_add_f32 v[40:41], v[126:127], 1.0 op_sel_hi:[1, 0]
	v_pk_fma_f32 v[34:35], v[34:35], v[38:39], v[128:129]
	v_pk_fma_f32 v[36:37], v[36:37], v[40:41], v[130:131]
	v_cvt_pk_bf16_f32 v34, v34, v35
	v_pk_mul_f32 v[58:59], v[28:29], v[28:29]
	v_cvt_pk_bf16_f32 v35, v36, v37
	global_store_dwordx2 v[46:47], v[34:35], off offset:512
	s_nop 0
	v_pk_mul_f32 v[60:61], v[26:27], v[26:27]
	v_pk_mul_f32 v[34:35], v[54:55], v[132:133]
	v_pk_add_f32 v[38:39], v[136:137], 1.0 op_sel_hi:[1, 0]
	v_pk_mul_f32 v[36:37], v[56:57], v[134:135]
	v_pk_add_f32 v[40:41], v[138:139], 1.0 op_sel_hi:[1, 0]
	v_pk_fma_f32 v[34:35], v[34:35], v[38:39], v[140:141]
	v_pk_fma_f32 v[36:37], v[36:37], v[40:41], v[142:143]
	v_cvt_pk_bf16_f32 v34, v34, v35
	v_pk_mul_f32 v[54:55], v[32:33], v[32:33]
	v_cvt_pk_bf16_f32 v35, v36, v37
	global_store_dwordx2 v[46:47], v[34:35], off offset:1024
	s_nop 0
	v_pk_mul_f32 v[56:57], v[30:31], v[30:31]
	v_pk_mul_f32 v[36:37], v[52:53], v[146:147]
	v_pk_mov_b32 v[88:89], v[56:57], v[54:55] op_sel:[1, 0]
	v_mov_b32_e32 v57, v55
	v_pk_add_f32 v[56:57], v[88:89], v[56:57]
	v_pk_add_f32 v[38:39], v[148:149], 1.0 op_sel_hi:[1, 0]
	v_pk_add_f32 v[56:57], v[56:57], v[56:57] op_sel:[0, 1] op_sel_hi:[1, 0]
	v_pk_add_f32 v[40:41], v[150:151], 1.0 op_sel_hi:[1, 0]
	v_mov_b32_e32 v57, v49
	v_pk_mul_f32 v[48:49], v[50:51], v[48:49] op_sel_hi:[1, 0]
	v_pk_fma_f32 v[36:37], v[36:37], v[40:41], v[154:155]
	v_pk_mul_f32 v[34:35], v[48:49], v[144:145]
	v_pk_mov_b32 v[54:55], v[60:61], v[58:59] op_sel:[1, 0]
	v_pk_fma_f32 v[34:35], v[34:35], v[38:39], v[152:153]
	v_mov_b32_e32 v61, v59
	v_cvt_pk_bf16_f32 v34, v34, v35
	v_cvt_pk_bf16_f32 v35, v36, v37
	global_store_dwordx2 v[46:47], v[34:35], off offset:1536
	v_pk_add_f32 v[54:55], v[54:55], v[60:61]
	v_pk_fma_f32 v[58:59], v[22:23], v[22:23], v[62:63] op_sel_hi:[1, 1, 0]
	v_pk_fma_f32 v[62:63], v[24:25], v[24:25], v[64:65] op_sel_hi:[1, 1, 0]
	v_pk_add_f32 v[54:55], v[54:55], v[54:55] op_sel:[0, 1] op_sel_hi:[1, 0]
	v_mov_b32_e32 v59, v87
	v_mov_b32_e32 v63, v90
	v_mov_b32_e32 v55, v65
	v_pk_add_f32 v[58:59], v[58:59], v[62:63]
	v_pk_add_f32 v[46:47], v[56:57], v[54:55]
	s_nop 0
	v_pk_add_f32 v[46:47], v[46:47], v[58:59]
	s_nop 0
	v_add_f32_e32 v46, v46, v47
	ds_bpermute_b32 v47, v0, v46
	s_waitcnt lgkmcnt(0)
	v_add_f32_e32 v46, v46, v47
	ds_bpermute_b32 v47, v82, v46
	s_waitcnt lgkmcnt(0)
	v_add_f32_e32 v46, v46, v47
	ds_bpermute_b32 v47, v83, v46
	s_waitcnt lgkmcnt(0)
	v_add_f32_e32 v46, v46, v47
	ds_bpermute_b32 v47, v84, v46
	s_waitcnt lgkmcnt(0)
	v_add_f32_e32 v46, v46, v47
	ds_bpermute_b32 v47, v85, v46
	s_waitcnt lgkmcnt(0)
	v_add_f32_e32 v46, v46, v47
	ds_bpermute_b32 v47, v86, v46
	s_waitcnt lgkmcnt(0)
	v_add_f32_e32 v46, v46, v47
	v_fmamk_f32 v46, v46, 0x3a800000, v207
	v_mul_f32_e32 v47, 0x4f800000, v46
	v_cmp_gt_f32_e32 vcc, s82, v46
	s_nop 1
	v_cndmask_b32_e32 v46, v46, v47, vcc
	v_sqrt_f32_e32 v47, v46
	s_nop 0
	v_add_u32_e32 v48, -1, v47
	v_add_u32_e32 v49, 1, v47
	v_fma_f32 v50, -v48, v47, v46
	v_fma_f32 v51, -v49, v47, v46
	v_cmp_ge_f32_e64 s[36:37], 0, v50
	s_nop 1
	v_cndmask_b32_e64 v47, v47, v48, s[36:37]
	v_cmp_lt_f32_e64 s[36:37], 0, v51
	s_nop 1
	v_cndmask_b32_e64 v47, v47, v49, s[36:37]
	v_mul_f32_e32 v48, 0x37800000, v47
	v_cndmask_b32_e32 v47, v47, v48, vcc
	v_cmp_class_f32_e32 vcc, v46, v227
	s_nop 1
	v_cndmask_b32_e32 v48, v47, v46, vcc
	v_div_scale_f32 v49, s[14:15], v48, v48, 1.0
	v_rcp_f32_e32 v50, v49
	v_div_scale_f32 v51, vcc, 1.0, v48, 1.0
	v_lshl_add_u64 v[46:47], v[68:69], 0, s[0:1]
	v_fma_f32 v52, -v49, v50, 1.0
	v_fmac_f32_e32 v50, v52, v50
	v_mul_f32_e32 v52, v51, v50
	v_fma_f32 v53, -v49, v52, v51
	v_fmac_f32_e32 v52, v53, v50
	v_fma_f32 v49, -v49, v52, v51
	v_div_fmas_f32 v49, v49, v50, v52
	v_div_fixup_f32 v48, v49, v48, 1.0
	v_pk_mul_f32 v[32:33], v[32:33], v[48:49] op_sel_hi:[1, 0]
	v_pk_mul_f32 v[30:31], v[30:31], v[48:49] op_sel_hi:[1, 0]
	v_pk_mul_f32 v[32:33], v[32:33], v[114:115]
	v_pk_mul_f32 v[30:31], v[30:31], v[112:113]
	v_pk_add_f32 v[36:37], v[108:109], 1.0 op_sel_hi:[1, 0]
	v_pk_add_f32 v[34:35], v[110:111], 1.0 op_sel_hi:[1, 0]
	v_pk_fma_f32 v[30:31], v[30:31], v[36:37], v[116:117]
	v_pk_fma_f32 v[32:33], v[32:33], v[34:35], v[118:119]
	v_cvt_pk_bf16_f32 v30, v30, v31
	v_pk_mul_f32 v[28:29], v[28:29], v[48:49] op_sel_hi:[1, 0]
	v_cvt_pk_bf16_f32 v31, v32, v33
	global_store_dwordx2 v[46:47], v[30:31], off
	s_nop 0
	v_pk_mul_f32 v[26:27], v[26:27], v[48:49] op_sel_hi:[1, 0]
	v_pk_mul_f32 v[24:25], v[24:25], v[48:49] op_sel_hi:[1, 0]
	v_pk_mul_f32 v[22:23], v[22:23], v[48:49] op_sel_hi:[1, 0]
	v_mul_f32_e32 v49, v3, v3
	v_pk_mul_f32 v[20:21], v[20:21], v[48:49] op_sel_hi:[1, 0]
	v_pk_mul_f32 v[18:19], v[18:19], v[48:49] op_sel_hi:[1, 0]
	v_mul_f32_e32 v45, v2, v2
	v_mul_f32_e32 v42, v7, v7
	v_mul_f32_e32 v44, v9, v9
	v_mul_f32_e32 v52, v4, v4
	v_mul_f32_e32 v53, v5, v5
	s_lshl_b64 s[0:1], s[10:11], 11
	v_pk_mul_f32 v[26:27], v[26:27], v[120:121]
	v_pk_mul_f32 v[28:29], v[28:29], v[122:123]
	v_pk_add_f32 v[32:33], v[124:125], 1.0 op_sel_hi:[1, 0]
	v_pk_add_f32 v[30:31], v[126:127], 1.0 op_sel_hi:[1, 0]
	v_pk_fma_f32 v[26:27], v[26:27], v[32:33], v[128:129]
	v_pk_fma_f32 v[28:29], v[28:29], v[30:31], v[130:131]
	v_cvt_pk_bf16_f32 v26, v26, v27
	v_pk_mul_f32 v[38:39], v[12:13], v[12:13]
	v_cvt_pk_bf16_f32 v27, v28, v29
	global_store_dwordx2 v[46:47], v[26:27], off offset:512
	s_nop 0
	v_pk_mul_f32 v[40:41], v[10:11], v[10:11]
	v_pk_mul_f32 v[22:23], v[22:23], v[132:133]
	v_pk_mul_f32 v[24:25], v[24:25], v[134:135]
	v_pk_add_f32 v[28:29], v[136:137], 1.0 op_sel_hi:[1, 0]
	v_pk_add_f32 v[26:27], v[138:139], 1.0 op_sel_hi:[1, 0]
	v_pk_fma_f32 v[22:23], v[22:23], v[28:29], v[140:141]
	v_pk_fma_f32 v[24:25], v[24:25], v[26:27], v[142:143]
	v_cvt_pk_bf16_f32 v22, v22, v23
	v_pk_mul_f32 v[34:35], v[16:17], v[16:17]
	v_cvt_pk_bf16_f32 v23, v24, v25
	global_store_dwordx2 v[46:47], v[22:23], off offset:1024
	s_nop 0
	v_pk_mul_f32 v[36:37], v[14:15], v[14:15]
	v_pk_mul_f32 v[18:19], v[18:19], v[144:145]
	v_pk_mul_f32 v[20:21], v[20:21], v[146:147]
	v_pk_add_f32 v[24:25], v[148:149], 1.0 op_sel_hi:[1, 0]
	v_pk_add_f32 v[22:23], v[150:151], 1.0 op_sel_hi:[1, 0]
	v_pk_fma_f32 v[18:19], v[18:19], v[24:25], v[152:153]
	v_pk_fma_f32 v[20:21], v[20:21], v[22:23], v[154:155]
	v_cvt_pk_bf16_f32 v18, v18, v19
	v_pk_mov_b32 v[50:51], v[36:37], v[34:35] op_sel:[1, 0]
	v_cvt_pk_bf16_f32 v19, v20, v21
	global_store_dwordx2 v[46:47], v[18:19], off offset:1536
	v_mov_b32_e32 v37, v35
	v_pk_mov_b32 v[34:35], v[40:41], v[38:39] op_sel:[1, 0]
	v_mov_b32_e32 v41, v39
	v_pk_add_f32 v[36:37], v[50:51], v[36:37]
	v_pk_add_f32 v[34:35], v[34:35], v[40:41]
	v_mov_b32_e32 v43, v117
	v_pk_fma_f32 v[38:39], v[6:7], v[6:7], v[42:43] op_sel_hi:[1, 1, 0]
	v_pk_fma_f32 v[42:43], v[8:9], v[8:9], v[44:45] op_sel_hi:[1, 1, 0]
	v_pk_add_f32 v[36:37], v[36:37], v[36:37] op_sel:[0, 1] op_sel_hi:[1, 0]
	v_pk_add_f32 v[34:35], v[34:35], v[34:35] op_sel:[0, 1] op_sel_hi:[1, 0]
	v_mov_b32_e32 v39, v52
	v_mov_b32_e32 v43, v53
	v_mov_b32_e32 v37, v45
	v_mov_b32_e32 v35, v49
	v_pk_add_f32 v[38:39], v[38:39], v[42:43]
	v_pk_add_f32 v[30:31], v[36:37], v[34:35]
	s_nop 0
	v_pk_add_f32 v[30:31], v[30:31], v[38:39]
	s_nop 0
	v_add_f32_e32 v30, v30, v31
	ds_bpermute_b32 v31, v0, v30
	s_waitcnt lgkmcnt(0)
	v_add_f32_e32 v30, v30, v31
	ds_bpermute_b32 v31, v82, v30
	s_waitcnt lgkmcnt(0)
	v_add_f32_e32 v30, v30, v31
	ds_bpermute_b32 v31, v83, v30
	s_waitcnt lgkmcnt(0)
	v_add_f32_e32 v30, v30, v31
	ds_bpermute_b32 v31, v84, v30
	s_waitcnt lgkmcnt(0)
	v_add_f32_e32 v30, v30, v31
	ds_bpermute_b32 v31, v85, v30
	s_waitcnt lgkmcnt(0)
	v_add_f32_e32 v30, v30, v31
	ds_bpermute_b32 v31, v86, v30
	s_waitcnt lgkmcnt(0)
	v_add_f32_e32 v30, v30, v31
	v_fmamk_f32 v30, v30, 0x3a800000, v207
	v_mul_f32_e32 v31, 0x4f800000, v30
	v_cmp_gt_f32_e32 vcc, s82, v30
	s_nop 1
	v_cndmask_b32_e32 v30, v30, v31, vcc
	v_sqrt_f32_e32 v31, v30
	s_nop 0
	v_add_u32_e32 v32, -1, v31
	v_add_u32_e32 v33, 1, v31
	v_fma_f32 v34, -v32, v31, v30
	v_fma_f32 v35, -v33, v31, v30
	v_cmp_ge_f32_e64 s[36:37], 0, v34
	s_nop 1
	v_cndmask_b32_e64 v31, v31, v32, s[36:37]
	v_cmp_lt_f32_e64 s[36:37], 0, v35
	s_nop 1
	v_cndmask_b32_e64 v31, v31, v33, s[36:37]
	v_mul_f32_e32 v32, 0x37800000, v31
	v_cndmask_b32_e32 v31, v31, v32, vcc
	v_cmp_class_f32_e32 vcc, v30, v227
	s_nop 1
	v_cndmask_b32_e32 v32, v31, v30, vcc
	v_div_scale_f32 v33, s[10:11], v32, v32, 1.0
	v_rcp_f32_e32 v34, v33
	v_div_scale_f32 v35, vcc, 1.0, v32, 1.0
	v_lshl_add_u64 v[30:31], v[68:69], 0, s[0:1]
	v_fma_f32 v36, -v33, v34, 1.0
	v_fmac_f32_e32 v34, v36, v34
	v_mul_f32_e32 v36, v35, v34
	v_fma_f32 v37, -v33, v36, v35
	v_fmac_f32_e32 v36, v37, v34
	v_fma_f32 v33, -v33, v36, v35
	v_div_fmas_f32 v33, v33, v34, v36
	v_div_fixup_f32 v32, v33, v32, 1.0
	v_pk_mul_f32 v[16:17], v[16:17], v[32:33] op_sel_hi:[1, 0]
	v_pk_mul_f32 v[14:15], v[14:15], v[32:33] op_sel_hi:[1, 0]
	v_pk_mul_f32 v[16:17], v[16:17], v[114:115]
	v_pk_mul_f32 v[14:15], v[14:15], v[112:113]
	v_pk_add_f32 v[20:21], v[108:109], 1.0 op_sel_hi:[1, 0]
	v_pk_add_f32 v[18:19], v[110:111], 1.0 op_sel_hi:[1, 0]
	v_pk_fma_f32 v[14:15], v[14:15], v[20:21], v[116:117]
	v_pk_fma_f32 v[16:17], v[16:17], v[18:19], v[118:119]
	v_cvt_pk_bf16_f32 v14, v14, v15
	v_pk_mul_f32 v[12:13], v[12:13], v[32:33] op_sel_hi:[1, 0]
	v_cvt_pk_bf16_f32 v15, v16, v17
	global_store_dwordx2 v[30:31], v[14:15], off
	s_nop 0
	v_pk_mul_f32 v[10:11], v[10:11], v[32:33] op_sel_hi:[1, 0]
	v_pk_mul_f32 v[8:9], v[8:9], v[32:33] op_sel_hi:[1, 0]
	v_pk_mul_f32 v[6:7], v[6:7], v[32:33] op_sel_hi:[1, 0]
	v_pk_mul_f32 v[4:5], v[4:5], v[32:33] op_sel_hi:[1, 0]
	v_pk_mul_f32 v[2:3], v[2:3], v[32:33] op_sel_hi:[1, 0]
	v_pk_mul_f32 v[10:11], v[10:11], v[120:121]
	v_pk_mul_f32 v[12:13], v[12:13], v[122:123]
	v_pk_add_f32 v[16:17], v[124:125], 1.0 op_sel_hi:[1, 0]
	v_pk_add_f32 v[14:15], v[126:127], 1.0 op_sel_hi:[1, 0]
	v_pk_fma_f32 v[10:11], v[10:11], v[16:17], v[128:129]
	v_pk_fma_f32 v[12:13], v[12:13], v[14:15], v[130:131]
	v_cvt_pk_bf16_f32 v10, v10, v11
	s_nop 0
	v_cvt_pk_bf16_f32 v11, v12, v13
	global_store_dwordx2 v[30:31], v[10:11], off offset:512
	s_nop 0
	v_pk_mul_f32 v[6:7], v[6:7], v[132:133]
	v_pk_mul_f32 v[8:9], v[8:9], v[134:135]
	v_pk_add_f32 v[12:13], v[136:137], 1.0 op_sel_hi:[1, 0]
	v_pk_add_f32 v[10:11], v[138:139], 1.0 op_sel_hi:[1, 0]
	v_pk_fma_f32 v[6:7], v[6:7], v[12:13], v[140:141]
	v_pk_fma_f32 v[8:9], v[8:9], v[10:11], v[142:143]
	v_cvt_pk_bf16_f32 v6, v6, v7
	s_nop 0
	v_cvt_pk_bf16_f32 v7, v8, v9
	global_store_dwordx2 v[30:31], v[6:7], off offset:1024
	s_nop 0
	v_pk_mul_f32 v[2:3], v[2:3], v[144:145]
	v_pk_mul_f32 v[4:5], v[4:5], v[146:147]
	v_pk_add_f32 v[8:9], v[148:149], 1.0 op_sel_hi:[1, 0]
	v_pk_add_f32 v[6:7], v[150:151], 1.0 op_sel_hi:[1, 0]
	v_pk_fma_f32 v[2:3], v[2:3], v[8:9], v[152:153]
	v_pk_fma_f32 v[4:5], v[4:5], v[6:7], v[154:155]
	v_cvt_pk_bf16_f32 v2, v2, v3
	s_nop 0
	v_cvt_pk_bf16_f32 v3, v4, v5
	global_store_dwordx2 v[30:31], v[2:3], off offset:1536
	s_branch .LBB0_142

.LBB0_486:
	v_lshl_add_u64 v[162:163], v[152:153], 0, s[64:65]
	global_load_dwordx2 v[178:179], v[162:163], off offset:-256
	global_load_dwordx2 v[176:177], v[162:163], off offset:-192
	global_load_dwordx2 v[174:175], v[162:163], off offset:-128
	global_load_dwordx2 v[172:173], v[162:163], off offset:-64
	global_load_dwordx2 v[170:171], v[162:163], off
	global_load_dwordx2 v[168:169], v[162:163], off offset:64
	global_load_dwordx2 v[166:167], v[162:163], off offset:128
	global_load_dwordx2 v[164:165], v[162:163], off offset:192
	s_andn2_b64 vcc, exec, s[16:17]
	s_cbranch_vccnz .LBB0_488
	ds_read_b128 v[66:69], v0
	ds_read_b128 v[82:85], v0 offset:32
	ds_read_b128 v[70:73], v224 offset:17408
	ds_read_b128 v[86:89], v224 offset:17440
	ds_read_b128 v[90:93], v0 offset:64
	ds_read_b128 v[94:97], v224 offset:17472
	s_add_i32 s20, 0, 0x1d000
	s_movk_i32 s21, 0x7fff
	s_waitcnt lgkmcnt(3)
	v_mfma_f32_32x32x16_bf16 v[66:81], v[66:69], v[70:73], 0
	s_waitcnt lgkmcnt(2)
	v_mfma_f32_32x32x16_bf16 v[66:81], v[82:85], v[86:89], v[66:81]
	ds_read_b128 v[82:85], v0 offset:96
	ds_read_b128 v[86:89], v224 offset:17504
	s_waitcnt lgkmcnt(2)
	v_mfma_f32_32x32x16_bf16 v[66:81], v[90:93], v[94:97], v[66:81]
	ds_read_b128 v[90:93], v0 offset:128
	ds_read_b128 v[94:97], v224 offset:17536
	s_waitcnt lgkmcnt(2)
	v_mfma_f32_32x32x16_bf16 v[66:81], v[82:85], v[86:89], v[66:81]
	ds_read_b128 v[82:85], v0 offset:160
	ds_read_b128 v[86:89], v224 offset:17568
	s_waitcnt lgkmcnt(2)
	v_mfma_f32_32x32x16_bf16 v[66:81], v[90:93], v[94:97], v[66:81]
	ds_read_b128 v[90:93], v0 offset:192
	ds_read_b128 v[94:97], v224 offset:17600
	s_waitcnt lgkmcnt(2)
	v_mfma_f32_32x32x16_bf16 v[66:81], v[82:85], v[86:89], v[66:81]
	ds_read_b128 v[82:85], v0 offset:224
	ds_read_b128 v[86:89], v224 offset:17632
	s_waitcnt lgkmcnt(2)
	v_mfma_f32_32x32x16_bf16 v[66:81], v[90:93], v[94:97], v[66:81]
	s_waitcnt lgkmcnt(0)
	v_mfma_f32_32x32x16_bf16 v[66:81], v[82:85], v[86:89], v[66:81]
	v_add_u32_e32 v82, s20, v197
	ds_read_b32 v82, v82
	v_add_u32_e32 v83, s20, v198
	ds_read_b32 v83, v83
	v_add_u32_e32 v84, s20, v199
	ds_read_b32 v84, v84
	v_add_u32_e32 v85, s20, v200
	ds_read_b32 v85, v85
	v_add_u32_e32 v86, s20, v201
	ds_read_b32 v86, v86
	v_add_u32_e32 v87, s20, v202
	ds_read_b32 v87, v87
	v_add_u32_e32 v88, s20, v203
	ds_read_b32 v88, v88
	v_add_u32_e32 v89, s20, v204
	ds_read_b32 v89, v89
	v_add_u32_e32 v90, s20, v205
	ds_read_b32 v90, v90
	v_add_u32_e32 v91, s20, v216
	ds_read_b32 v91, v91
	v_add_u32_e32 v92, s20, v217
	ds_read_b32 v92, v92
	v_add_u32_e32 v93, s20, v218
	ds_read_b32 v93, v93
	v_add_u32_e32 v94, s20, v219
	ds_read_b32 v94, v94
	v_add_u32_e32 v95, s20, v220
	ds_read_b32 v95, v95
	v_add_u32_e32 v96, s20, v221
	ds_read_b32 v96, v96
	v_add_u32_e32 v97, s20, v222
	ds_read_b32 v97, v97
	s_waitcnt lgkmcnt(0)
	v_mul_f32_e32 v66, v66, v82
	v_mul_f32_e32 v67, v67, v83
	v_mul_f32_e32 v68, v68, v84
	v_mul_f32_e32 v69, v69, v85
	v_mul_f32_e32 v70, v70, v86
	v_mul_f32_e32 v71, v71, v87
	v_mul_f32_e32 v72, v72, v88
	v_mul_f32_e32 v73, v73, v89
	v_mul_f32_e32 v74, v74, v90
	v_mul_f32_e32 v75, v75, v91
	v_mul_f32_e32 v76, v76, v92
	v_mul_f32_e32 v77, v77, v93
	v_mul_f32_e32 v78, v78, v94
	v_mul_f32_e32 v79, v79, v95
	v_mul_f32_e32 v80, v80, v96
	v_mul_f32_e32 v81, v81, v97
	v_bfe_u32 v82, v66, 16, 1
	v_bfe_u32 v83, v67, 16, 1
	v_bfe_u32 v84, v68, 16, 1
	v_bfe_u32 v85, v69, 16, 1
	v_bfe_u32 v86, v70, 16, 1
	v_bfe_u32 v87, v71, 16, 1
	v_bfe_u32 v88, v72, 16, 1
	v_bfe_u32 v89, v73, 16, 1
	v_bfe_u32 v90, v74, 16, 1
	v_bfe_u32 v91, v75, 16, 1
	v_bfe_u32 v92, v76, 16, 1
	v_bfe_u32 v93, v77, 16, 1
	v_bfe_u32 v94, v78, 16, 1
	v_bfe_u32 v95, v79, 16, 1
	v_bfe_u32 v96, v80, 16, 1
	v_bfe_u32 v97, v81, 16, 1
	v_add3_u32 v66, v66, v82, s21
	v_add3_u32 v67, v67, v83, s21
	v_add3_u32 v68, v68, v84, s21
	v_add3_u32 v69, v69, v85, s21
	v_add3_u32 v70, v70, v86, s21
	v_add3_u32 v71, v71, v87, s21
	v_add3_u32 v72, v72, v88, s21
	v_add3_u32 v73, v73, v89, s21
	v_add3_u32 v74, v74, v90, s21
	v_add3_u32 v75, v75, v91, s21
	v_add3_u32 v76, v76, v92, s21
	v_add3_u32 v77, v77, v93, s21
	v_add3_u32 v78, v78, v94, s21
	v_add3_u32 v79, v79, v95, s21
	v_add3_u32 v80, v80, v96, s21
	v_add3_u32 v81, v81, v97, s21
	ds_write_b16_d16_hi v225, v66
	ds_write_b16_d16_hi v225, v67 offset:144
	ds_write_b16_d16_hi v225, v68 offset:288
	ds_write_b16_d16_hi v225, v69 offset:432
	ds_write_b16_d16_hi v225, v70 offset:1152
	ds_write_b16_d16_hi v225, v71 offset:1296
	ds_write_b16_d16_hi v225, v72 offset:1440
	ds_write_b16_d16_hi v225, v73 offset:1584
	ds_write_b16_d16_hi v225, v74 offset:2304
	ds_write_b16_d16_hi v225, v75 offset:2448
	ds_write_b16_d16_hi v225, v76 offset:2592
	ds_write_b16_d16_hi v225, v77 offset:2736
	ds_write_b16_d16_hi v225, v78 offset:3456
	ds_write_b16_d16_hi v225, v79 offset:3600
	ds_write_b16_d16_hi v225, v80 offset:3744
	ds_write_b16_d16_hi v225, v81 offset:3888
